# v8 + removed the per-unit header vmcnt(0) in the QKV and residual GEMM unit loops
# speedup vs baseline: 1.0000x; 1.0000x over previous
; template <class Epi, class Sched, bool ALIGN_EPI = false, bool SP2 = false>
; __device__ __forceinline__ void gemm_phase(PG8_LAS unsigned char* lds, const Gemm g, const Sched& S, const Epi& E, int tid_in) {
;     ...
;         const bool has_next = S.next(ui + 1, nxt);
;         const char* nA = has_next ? (const char*)g.A + (size_t)nxt.pm * tstep : cA; const char* nB = has_next ? (const char*)g.Bt + (size_t)nxt.pn * tstep : cB;
;     ...
; #pragma unroll
;         for (int a = 0; a < 2; ++a)
; #pragma unroll
;             for (int b = 0; b < 2; ++b)
; #pragma unroll
;                 for (int m = 0; m < 4; ++m)
; #pragma unroll
;                     for (int n = 0; n < 2; ++n) acc[a][b][m][n] = (f32x4){0.f, 0.f, 0.f, 0.f};
.LBB0_439:
	s_ashr_i32 s9, s8, 31
	s_lshl_b64 s[72:73], s[8:9], 19
	s_add_u32 s10, s29, s72
	s_addc_u32 s11, s31, s73
	s_and_b64 s[74:75], s[36:37], exec
	s_cselect_b32 s71, s11, s79
	s_cselect_b32 s77, s10, s78
	s_ashr_i32 s67, s66, 31
	s_lshl_b64 s[74:75], s[66:67], 19
	v_readlane_b32 s9, v254, 4
	s_add_u32 s12, s9, s74
	v_readlane_b32 s9, v254, 6
	s_addc_u32 s13, s9, s75
	s_and_b64 s[82:83], s[36:37], exec
	s_cselect_b32 s67, s13, s81
	s_cselect_b32 s84, s12, s80
	s_add_u32 s78, s78, 0x40080
	s_addc_u32 s79, s79, 0
	s_add_u32 s85, s80, 0x100
	v_mov_b32_e32 v0, 0
	s_addc_u32 s86, s81, 0
	s_mov_b32 s87, -2
	v_mov_b32_e32 v1, v0
	v_mov_b32_e32 v2, v0
	v_mov_b32_e32 v3, v0
	v_mov_b32_e32 v4, v0
	v_mov_b32_e32 v5, v0
	v_mov_b32_e32 v6, v0
	v_mov_b32_e32 v7, v0
	v_mov_b32_e32 v16, v0
	v_mov_b32_e32 v17, v0
	v_mov_b32_e32 v18, v0
	v_mov_b32_e32 v19, v0
	v_mov_b32_e32 v20, v0
	v_mov_b32_e32 v21, v0
	v_mov_b32_e32 v22, v0
	v_mov_b32_e32 v23, v0
	v_mov_b32_e32 v32, v0
	v_mov_b32_e32 v33, v0
	v_mov_b32_e32 v34, v0
	v_mov_b32_e32 v35, v0
	v_mov_b32_e32 v36, v0
	v_mov_b32_e32 v37, v0
	v_mov_b32_e32 v38, v0
	v_mov_b32_e32 v39, v0
	v_mov_b32_e32 v48, v0
	v_mov_b32_e32 v49, v0
	v_mov_b32_e32 v50, v0
	v_mov_b32_e32 v51, v0
	v_mov_b32_e32 v52, v0
	v_mov_b32_e32 v53, v0
	v_mov_b32_e32 v54, v0
	v_mov_b32_e32 v55, v0
	v_mov_b32_e32 v8, v0
	v_mov_b32_e32 v9, v0
	v_mov_b32_e32 v10, v0
	v_mov_b32_e32 v11, v0
	v_mov_b32_e32 v12, v0
	v_mov_b32_e32 v13, v0
	v_mov_b32_e32 v14, v0
	v_mov_b32_e32 v15, v0
	v_mov_b32_e32 v24, v0
	v_mov_b32_e32 v25, v0
	v_mov_b32_e32 v26, v0
	v_mov_b32_e32 v27, v0
	v_mov_b32_e32 v28, v0
	v_mov_b32_e32 v29, v0
	v_mov_b32_e32 v30, v0
	v_mov_b32_e32 v31, v0
	v_mov_b32_e32 v40, v0
	v_mov_b32_e32 v41, v0
	v_mov_b32_e32 v42, v0
	v_mov_b32_e32 v43, v0
	v_mov_b32_e32 v44, v0
	v_mov_b32_e32 v45, v0
	v_mov_b32_e32 v46, v0
	v_mov_b32_e32 v47, v0
	v_mov_b32_e32 v56, v0
	v_mov_b32_e32 v57, v0
	v_mov_b32_e32 v58, v0
	v_mov_b32_e32 v59, v0
	v_mov_b32_e32 v60, v0
	v_mov_b32_e32 v61, v0
	v_mov_b32_e32 v62, v0
	v_mov_b32_e32 v63, v0
	v_mov_b32_e32 v64, v0
	v_mov_b32_e32 v65, v0
	v_mov_b32_e32 v66, v0
	v_mov_b32_e32 v67, v0
	v_mov_b32_e32 v68, v0
	v_mov_b32_e32 v69, v0
	v_mov_b32_e32 v70, v0
	v_mov_b32_e32 v71, v0
	v_mov_b32_e32 v82, v0
	v_mov_b32_e32 v83, v0
	v_mov_b32_e32 v84, v0
	v_mov_b32_e32 v85, v0
	v_mov_b32_e32 v86, v0
	v_mov_b32_e32 v87, v0
	v_mov_b32_e32 v88, v0
	v_mov_b32_e32 v89, v0
	v_mov_b32_e32 v94, v0
	v_mov_b32_e32 v95, v0
	v_mov_b32_e32 v96, v0
	v_mov_b32_e32 v97, v0
	v_mov_b32_e32 v102, v0
	v_mov_b32_e32 v103, v0
	v_mov_b32_e32 v104, v0
	v_mov_b32_e32 v105, v0
	v_mov_b32_e32 v110, v0
	v_mov_b32_e32 v111, v0
	v_mov_b32_e32 v112, v0
	v_mov_b32_e32 v113, v0
	v_mov_b32_e32 v118, v0
	v_mov_b32_e32 v119, v0
	v_mov_b32_e32 v120, v0
	v_mov_b32_e32 v121, v0
	v_mov_b32_e32 v72, v0
	v_mov_b32_e32 v73, v0
	v_mov_b32_e32 v74, v0
	v_mov_b32_e32 v75, v0
	v_mov_b32_e32 v76, v0
	v_mov_b32_e32 v77, v0
	v_mov_b32_e32 v78, v0
	v_mov_b32_e32 v79, v0
	v_mov_b32_e32 v90, v0
	v_mov_b32_e32 v91, v0
	v_mov_b32_e32 v92, v0
	v_mov_b32_e32 v93, v0
	v_mov_b32_e32 v98, v0
	v_mov_b32_e32 v99, v0
	v_mov_b32_e32 v100, v0
	v_mov_b32_e32 v101, v0
	v_mov_b32_e32 v106, v0
	v_mov_b32_e32 v107, v0
	v_mov_b32_e32 v108, v0
	v_mov_b32_e32 v109, v0
	v_mov_b32_e32 v114, v0
	v_mov_b32_e32 v115, v0
	v_mov_b32_e32 v116, v0
	v_mov_b32_e32 v117, v0
	v_mov_b32_e32 v122, v0
	v_mov_b32_e32 v123, v0
	v_mov_b32_e32 v124, v0
	v_mov_b32_e32 v125, v0
	v_mov_b32_e32 v126, v0
	v_mov_b32_e32 v127, v0
	v_mov_b32_e32 v128, v0
	v_mov_b32_e32 v129, v0

; template <class Epi, class Sched, bool ALIGN_EPI = false, bool SP2 = false>
; __device__ __forceinline__ void gemm_phase(PG8_LAS unsigned char* lds, const Gemm g, const Sched& S, const Epi& E, int tid_in) {
;     ...
;         const bool has_next = S.next(ui + 1, nxt);
;         const char* nA = has_next ? (const char*)g.A + (size_t)nxt.pm * tstep : cA; const char* nB = has_next ? (const char*)g.Bt + (size_t)nxt.pn * tstep : cB;
;     ...
; #pragma unroll
;         for (int a = 0; a < 2; ++a)
; #pragma unroll
;             for (int b = 0; b < 2; ++b)
; #pragma unroll
;                 for (int m = 0; m < 4; ++m)
; #pragma unroll
;                     for (int n = 0; n < 2; ++n) acc[a][b][m][n] = (f32x4){0.f, 0.f, 0.f, 0.f};
.LBB0_507:
	s_add_u32 s40, s92, 0x80
	s_addc_u32 s41, s93, 0
	s_add_u32 s26, s42, 0x100
	v_mov_b32_e32 v0, 0
	s_addc_u32 s27, s43, 0
	s_mov_b32 s42, 0
	s_waitcnt lgkmcnt(0)
	v_mov_b32_e32 v1, v0
	v_mov_b32_e32 v2, v0
	v_mov_b32_e32 v3, v0
	v_mov_b32_e32 v4, v0
	v_mov_b32_e32 v5, v0
	v_mov_b32_e32 v6, v0
	v_mov_b32_e32 v7, v0
	v_mov_b32_e32 v16, v0
	v_mov_b32_e32 v17, v0
	v_mov_b32_e32 v18, v0
	v_mov_b32_e32 v19, v0
	v_mov_b32_e32 v20, v0
	v_mov_b32_e32 v21, v0
	v_mov_b32_e32 v22, v0
	v_mov_b32_e32 v23, v0
	v_mov_b32_e32 v32, v0
	v_mov_b32_e32 v33, v0
	v_mov_b32_e32 v34, v0
	v_mov_b32_e32 v35, v0
	v_mov_b32_e32 v36, v0
	v_mov_b32_e32 v37, v0
	v_mov_b32_e32 v38, v0
	v_mov_b32_e32 v39, v0
	v_mov_b32_e32 v64, v0
	v_mov_b32_e32 v65, v0
	v_mov_b32_e32 v66, v0
	v_mov_b32_e32 v67, v0
	v_mov_b32_e32 v68, v0
	v_mov_b32_e32 v69, v0
	v_mov_b32_e32 v70, v0
	v_mov_b32_e32 v71, v0
	v_mov_b32_e32 v8, v0
	v_mov_b32_e32 v9, v0
	v_mov_b32_e32 v10, v0
	v_mov_b32_e32 v11, v0
	v_mov_b32_e32 v12, v0
	v_mov_b32_e32 v13, v0
	v_mov_b32_e32 v14, v0
	v_mov_b32_e32 v15, v0
	v_mov_b32_e32 v24, v0
	v_mov_b32_e32 v25, v0
	v_mov_b32_e32 v26, v0
	v_mov_b32_e32 v27, v0
	v_mov_b32_e32 v28, v0
	v_mov_b32_e32 v29, v0
	v_mov_b32_e32 v30, v0
	v_mov_b32_e32 v31, v0
	v_mov_b32_e32 v48, v0
	v_mov_b32_e32 v49, v0
	v_mov_b32_e32 v50, v0
	v_mov_b32_e32 v51, v0
	v_mov_b32_e32 v56, v0
	v_mov_b32_e32 v57, v0
	v_mov_b32_e32 v58, v0
	v_mov_b32_e32 v59, v0
	v_mov_b32_e32 v72, v0
	v_mov_b32_e32 v73, v0
	v_mov_b32_e32 v74, v0
	v_mov_b32_e32 v75, v0
	v_mov_b32_e32 v76, v0
	v_mov_b32_e32 v77, v0
	v_mov_b32_e32 v78, v0
	v_mov_b32_e32 v79, v0
	v_mov_b32_e32 v82, v0
	v_mov_b32_e32 v83, v0
	v_mov_b32_e32 v84, v0
	v_mov_b32_e32 v85, v0
	v_mov_b32_e32 v86, v0
	v_mov_b32_e32 v87, v0
	v_mov_b32_e32 v88, v0
	v_mov_b32_e32 v89, v0
	v_mov_b32_e32 v98, v0
	v_mov_b32_e32 v99, v0
	v_mov_b32_e32 v100, v0
	v_mov_b32_e32 v101, v0
	v_mov_b32_e32 v102, v0
	v_mov_b32_e32 v103, v0
	v_mov_b32_e32 v104, v0
	v_mov_b32_e32 v105, v0
	v_mov_b32_e32 v114, v0
	v_mov_b32_e32 v115, v0
	v_mov_b32_e32 v116, v0
	v_mov_b32_e32 v117, v0
	v_mov_b32_e32 v118, v0
	v_mov_b32_e32 v119, v0
	v_mov_b32_e32 v120, v0
	v_mov_b32_e32 v121, v0
	v_mov_b32_e32 v130, v0
	v_mov_b32_e32 v131, v0
	v_mov_b32_e32 v132, v0
	v_mov_b32_e32 v133, v0
	v_mov_b32_e32 v134, v0
	v_mov_b32_e32 v135, v0
	v_mov_b32_e32 v136, v0
	v_mov_b32_e32 v137, v0
	v_mov_b32_e32 v90, v0
	v_mov_b32_e32 v91, v0
	v_mov_b32_e32 v92, v0
	v_mov_b32_e32 v93, v0
	v_mov_b32_e32 v94, v0
	v_mov_b32_e32 v95, v0
	v_mov_b32_e32 v96, v0
	v_mov_b32_e32 v97, v0
	v_mov_b32_e32 v106, v0
	v_mov_b32_e32 v107, v0
	v_mov_b32_e32 v108, v0
	v_mov_b32_e32 v109, v0
	v_mov_b32_e32 v110, v0
	v_mov_b32_e32 v111, v0
	v_mov_b32_e32 v112, v0
	v_mov_b32_e32 v113, v0
	v_mov_b32_e32 v122, v0
	v_mov_b32_e32 v123, v0
	v_mov_b32_e32 v124, v0
	v_mov_b32_e32 v125, v0
	v_mov_b32_e32 v126, v0
	v_mov_b32_e32 v127, v0
	v_mov_b32_e32 v128, v0
	v_mov_b32_e32 v129, v0
	v_mov_b32_e32 v138, v0
	v_mov_b32_e32 v139, v0
	v_mov_b32_e32 v140, v0
	v_mov_b32_e32 v141, v0
	v_mov_b32_e32 v142, v0
	v_mov_b32_e32 v143, v0
	v_mov_b32_e32 v144, v0
	v_mov_b32_e32 v145, v0
